# diff-attention loop head: first PV MFMA of each step issued before the deferred row-max check (check runs in its shadow; rare paths out of line)
# baseline (speedup 1.0000x reference)
.Lhd_bar:
	s_barrier
	s_andn2_b64 vcc, exec, s[0:1]
	s_cbranch_vccz .Lslow_head
	s_add_i32 s20, s2, 0xffffc000
	s_and_b32 s20, s20, 0xc000
	v_add_u32_e32 v238, s20, v234
	s_add_i32 s20, s65, s20
	s_waitcnt lgkmcnt(1)
	v_mfma_f32_32x32x16_bf16 v[0:15], v[160:163], v[128:131], v[0:15]
	s_waitcnt lgkmcnt(0)
	v_max_f32_e32 v96, v100, v101
	v_cmp_lt_f32_e32 vcc, s67, v96
	s_cmp_lg_u64 vcc, 0
	s_cselect_b64 s[0:1], -1, 0
	s_cbranch_vccnz .LBB0_521b
.Lafter_pv1:
	ds_read_b64_tr_b16 v[196:197], v238
	ds_read_b64_tr_b16 v[198:199], v238 offset:512
	v_add_u32_e32 v96, s20, v228
	v_add_u32_e32 v97, s20, v229
	v_add_u32_e32 v98, s20, v230
	v_add_u32_e32 v99, s20, v231
	v_exp_f32_e32 v241, v80
	v_exp_f32_e32 v242, v81
	v_mfma_f32_32x32x16_bf16 v[0:15], v[164:167], v[132:135], v[0:15]
	ds_read_b64_tr_b16 v[192:193], v238 offset:1024
	ds_read_b64_tr_b16 v[194:195], v238 offset:1536
	v_exp_f32_e32 v243, v82
	v_exp_f32_e32 v244, v83
	s_add_i32 s22, s76, 4
	s_cmp_ge_u32 s22, s19
	s_cbranch_scc1 .LstgK_skip
	s_and_b64 s[38:39], s[16:17], exec
	s_cselect_b32 s22, s22, s3
	s_ashr_i32 s23, s22, 31
	s_lshl_b64 s[22:23], s[22:23], 16
	s_add_u32 s22, s74, s22
	s_addc_u32 s23, s75, s23
	s_add_i32 s38, s2, 0x8000
	s_and_b32 s38, s38, 0xc000
	s_add_i32 s38, s54, s38
	s_mov_b32 s39, m0
	s_mov_b32 m0, s38
	s_nop 0
	global_load_lds_dwordx4 v204, s[22:23]
	s_mov_b32 m0, s39
	s_add_u32 s22, s22, 0x80
	s_addc_u32 s23, s23, 0
	s_addk_i32 s38, 0x2000
	s_mov_b32 s39, m0
	s_mov_b32 m0, s38
	s_nop 0
	global_load_lds_dwordx4 v204, s[22:23]
	s_mov_b32 m0, s39

.Lslow_head:
	s_waitcnt lgkmcnt(0)
	v_max_f32_e32 v96, v100, v101
	s_branch .LBB0_518
.LBB0_508:
.LBB0_509:
	s_add_i32 s20, s2, 0xffffc000
	s_and_b32 s20, s20, 0xc000
	v_add_u32_e32 v238, s20, v234
	s_add_i32 s20, s65, s20
	v_mfma_f32_32x32x16_bf16 v[0:15], v[160:163], v[128:131], v[0:15]
	s_branch .Lafter_pv1
.LBB0_521b:
	v_max_f32_e32 v64, v96, v96
	v_max_f32_e32 v65, 0, v64
	v_exp_f32_e64 v232, -v65
	v_add_f32_e32 v233, v233, v65
	v_xor_b32_e32 v64, 0x80000000, v233
	v_sub_f32_e32 v95, v95, v65
	v_sub_f32_e32 v94, v94, v65
	v_sub_f32_e32 v93, v93, v65
	v_sub_f32_e32 v92, v92, v65
	v_sub_f32_e32 v91, v91, v65
	v_sub_f32_e32 v90, v90, v65
	v_sub_f32_e32 v89, v89, v65
	v_sub_f32_e32 v88, v88, v65
	v_sub_f32_e32 v87, v87, v65
	v_sub_f32_e32 v86, v86, v65
	v_sub_f32_e32 v85, v85, v65
	v_sub_f32_e32 v84, v84, v65
	v_sub_f32_e32 v83, v83, v65
	v_sub_f32_e32 v82, v82, v65
	v_sub_f32_e32 v81, v81, v65
	v_sub_f32_e32 v80, v80, v65
	v_mul_f32_e32 v235, v235, v232
	v_mov_b32_e32 v65, v64
	v_mov_b32_e32 v66, v64
	v_mov_b32_e32 v67, v64
	v_mov_b32_e32 v68, v64
	v_mov_b32_e32 v69, v64
	v_mov_b32_e32 v70, v64
	v_mov_b32_e32 v71, v64
	v_mov_b32_e32 v72, v64
	v_mov_b32_e32 v73, v64
	v_mov_b32_e32 v74, v64
	v_mov_b32_e32 v75, v64
	v_mov_b32_e32 v76, v64
	v_mov_b32_e32 v77, v64
	v_mov_b32_e32 v78, v64
	v_mov_b32_e32 v79, v64
	s_branch .Lafter_pv1
.Lhd_w0:
	s_waitcnt vmcnt(0)
	s_branch .Lhd_bar
